# K=1024 sample-row skinny GEMMs (P9, P14, P11): all 48 operand loads issued up front instead of a 6-deep window
# baseline (speedup 1.0000x reference)
; template <bool PAIR, class F>
; __device__ __forceinline__ void skinny(const bf16_t* A, int lda, const bf16_t* Bt, int ldb, int K, int tile_lo, int tile_hi, int kmode, int bx, int G, int tid_, LAS unsigned char* lds, F f) {
;     ...
;     for (int un = G - 1 - bx; un < nunits; un += G) {
;         const int rbp = un & 3, cgrp = un >> 2, tile = tile_lo + cgrp / GPT, cgp = (cgrp % GPT) * 4 + cgl;
;         const int n0 = tile * 256 + cgp * 16, row0 = MP + rbp * 32 + fr;
;         const bf16_t* ap = A + (size_t)row0 * lda + (kmode ? 256 * (tile >> 1) : 0) + fq * 8;
;         const bf16_t* bp = Bt + (size_t)(n0 + fr) * ldb + fq * 8;
;         f32x4 a00 = (f32x4){0.f, 0.f, 0.f, 0.f}, a01 = a00, a10 = a00, a11 = a00;
;         for (int k0 = kbeg; k0 < kbeg + Kh; k0 += 128) {
; #pragma unroll
;             for (int kk = 0; kk < 128; kk += 32) {
;                 const bf16x8 x0 = *(const bf16x8*)(ap + k0 + kk), x1 = *(const bf16x8*)(ap + (size_t)16 * lda + k0 + kk), b = *(const bf16x8*)(bp + k0 + kk);
;                 a00 = __builtin_amdgcn_mfma_f32_16x16x32_bf16(b, x0, a00, 0, 0, 0); a01 = __builtin_amdgcn_mfma_f32_16x16x32_bf16(b, x1, a01, 0, 0, 0);
;                 if (PAIR) { const bf16x8 b2 = *(const bf16x8*)(bp + (size_t)128 * ldb + k0 + kk);
;                     a10 = __builtin_amdgcn_mfma_f32_16x16x32_bf16(b2, x0, a10, 0, 0, 0); a11 = __builtin_amdgcn_mfma_f32_16x16x32_bf16(b2, x1, a11, 0, 0, 0); }
;             }
;         }
;         if (kh == 1) { X[0] = a00; X[1] = a01; if (PAIR) { X[2] = a10; X[3] = a11; } }
;         __syncthreads();
.LBB0_1267:
	s_ashr_i32 s28, s37, 2
	s_lshr_b32 s29, s28, 30
	s_add_i32 s38, s28, s29
	s_and_b32 s29, s38, 0x3fffffc
	s_sub_i32 s28, s28, s29
	s_lshl_b32 s28, s28, 6
	s_or_b32 s29, s28, s13
	s_and_b32 s28, s27, 0x60
	v_or_b32_e32 v0, s28, v16
	s_lshl_b32 s28, s38, 6
	s_and_b32 s28, s28, 0xffffff00
	s_add_i32 s38, s29, s28
	v_lshlrev_b32_e32 v19, 10, v0
	v_or_b32_e32 v0, s38, v16
	v_ashrrev_i32_e32 v1, 31, v0
	v_lshlrev_b64 v[0:1], 11, v[0:1]
	v_lshl_add_u64 v[64:65], v[12:13], 0, v[0:1]
	v_or_b32_e32 v14, 0x1000000, v19
	v_lshlrev_b32_e32 v8, 1, v14
	v_lshl_add_u64 v[230:231], v[10:11], 0, v[8:9]
	v_lshl_add_u64 v[232:233], v[230:231], 0, s[24:25]
	v_lshl_add_u64 v[234:235], v[230:231], 0, s[22:23]
	v_lshl_add_u64 v[236:237], v[234:235], 0, s[24:25]
	v_lshl_add_u64 v[238:239], s[16:17], 1, v[234:235]
	s_and_b64 vcc, exec, s[2:3]
	v_lshl_add_u64 v[240:241], s[18:19], 1, v[234:235]
	v_lshl_add_u64 v[242:243], s[20:21], 1, v[234:235]
	global_load_dwordx4 v[20:23], v[64:65], off
	global_load_dwordx4 v[24:27], v[232:233], off
	global_load_dwordx4 v[28:31], v[236:237], off
	global_load_dwordx4 v[32:35], v[64:65], off offset:64
	global_load_dwordx4 v[36:39], v[232:233], off offset:64
	global_load_dwordx4 v[40:43], v[236:237], off offset:64
	global_load_dwordx4 v[44:47], v[64:65], off offset:128
	global_load_dwordx4 v[48:51], v[232:233], off offset:128
	global_load_dwordx4 v[52:55], v[236:237], off offset:128
	global_load_dwordx4 v[56:59], v[64:65], off offset:192
	global_load_dwordx4 v[60:63], v[232:233], off offset:192
	global_load_dwordx4 v[66:69], v[236:237], off offset:192
	global_load_dwordx4 v[78:81], v[238:239], off
	global_load_dwordx4 v[82:85], v[64:65], off offset:256
	global_load_dwordx4 v[86:89], v[232:233], off offset:256
	global_load_dwordx4 v[90:93], v[64:65], off offset:320
	global_load_dwordx4 v[94:97], v[232:233], off offset:320
	global_load_dwordx4 v[98:101], v[64:65], off offset:384
	global_load_dwordx4 v[102:105], v[238:239], off offset:64
	global_load_dwordx4 v[106:109], v[232:233], off offset:384
	global_load_dwordx4 v[110:113], v[238:239], off offset:128
	global_load_dwordx4 v[114:117], v[64:65], off offset:448
	global_load_dwordx4 v[118:121], v[232:233], off offset:448
	global_load_dwordx4 v[122:125], v[238:239], off offset:192
	global_load_dwordx4 v[126:129], v[64:65], off offset:512
	global_load_dwordx4 v[130:133], v[232:233], off offset:512
	global_load_dwordx4 v[134:137], v[240:241], off
	global_load_dwordx4 v[138:141], v[64:65], off offset:576
	global_load_dwordx4 v[142:145], v[232:233], off offset:576
	global_load_dwordx4 v[146:149], v[240:241], off offset:64
	global_load_dwordx4 v[150:153], v[64:65], off offset:640
	global_load_dwordx4 v[154:157], v[232:233], off offset:640
	global_load_dwordx4 v[158:161], v[240:241], off offset:128
	global_load_dwordx4 v[162:165], v[64:65], off offset:704
	global_load_dwordx4 v[166:169], v[232:233], off offset:704
	global_load_dwordx4 v[170:173], v[240:241], off offset:192
	global_load_dwordx4 v[174:177], v[64:65], off offset:768
	global_load_dwordx4 v[178:181], v[232:233], off offset:768
	global_load_dwordx4 v[182:185], v[242:243], off
	global_load_dwordx4 v[190:193], v[64:65], off offset:832
	global_load_dwordx4 v[194:197], v[232:233], off offset:832
	global_load_dwordx4 v[198:201], v[242:243], off offset:64
	global_load_dwordx4 v[204:207], v[64:65], off offset:896
	global_load_dwordx4 v[208:211], v[232:233], off offset:896
	global_load_dwordx4 v[212:215], v[242:243], off offset:128
	global_load_dwordx4 v[216:219], v[64:65], off offset:960
	global_load_dwordx4 v[220:223], v[232:233], off offset:960
	global_load_dwordx4 v[224:227], v[242:243], off offset:192
	s_waitcnt vmcnt(46)
	v_mfma_f32_16x16x32_bf16 v[4:7], v[20:23], v[24:27], 0
	s_waitcnt vmcnt(45)
	v_mfma_f32_16x16x32_bf16 v[0:3], v[20:23], v[28:31], 0
	s_waitcnt vmcnt(43)
	v_mfma_f32_16x16x32_bf16 v[4:7], v[32:35], v[36:39], v[4:7]
	s_waitcnt vmcnt(42)
	v_mfma_f32_16x16x32_bf16 v[0:3], v[32:35], v[40:43], v[0:3]
	s_waitcnt vmcnt(40)
	v_mfma_f32_16x16x32_bf16 v[4:7], v[44:47], v[48:51], v[4:7]
	s_waitcnt vmcnt(39)
	v_mfma_f32_16x16x32_bf16 v[0:3], v[44:47], v[52:55], v[0:3]
	s_waitcnt vmcnt(37)
	v_mfma_f32_16x16x32_bf16 v[4:7], v[56:59], v[60:63], v[4:7]
	s_waitcnt vmcnt(36)
	v_mfma_f32_16x16x32_bf16 v[0:3], v[56:59], v[66:69], v[0:3]
	s_waitcnt vmcnt(33)
	v_mfma_f32_16x16x32_bf16 v[4:7], v[82:85], v[86:89], v[4:7]
	v_mfma_f32_16x16x32_bf16 v[0:3], v[82:85], v[78:81], v[0:3]
	s_waitcnt vmcnt(31)
	v_mfma_f32_16x16x32_bf16 v[4:7], v[90:93], v[94:97], v[4:7]
	s_waitcnt vmcnt(29)
	v_mfma_f32_16x16x32_bf16 v[0:3], v[90:93], v[102:105], v[0:3]
	s_waitcnt vmcnt(28)
	v_mfma_f32_16x16x32_bf16 v[4:7], v[98:101], v[106:109], v[4:7]
	s_waitcnt vmcnt(27)
	v_mfma_f32_16x16x32_bf16 v[0:3], v[98:101], v[110:113], v[0:3]
	s_waitcnt vmcnt(25)
	v_mfma_f32_16x16x32_bf16 v[4:7], v[114:117], v[118:121], v[4:7]
	s_waitcnt vmcnt(24)
	v_mfma_f32_16x16x32_bf16 v[0:3], v[114:117], v[122:125], v[0:3]
	s_waitcnt vmcnt(22)
	v_mfma_f32_16x16x32_bf16 v[4:7], v[126:129], v[130:133], v[4:7]
	s_waitcnt vmcnt(21)
	v_mfma_f32_16x16x32_bf16 v[0:3], v[126:129], v[134:137], v[0:3]
	s_waitcnt vmcnt(19)
	v_mfma_f32_16x16x32_bf16 v[4:7], v[138:141], v[142:145], v[4:7]
	s_waitcnt vmcnt(18)
	v_mfma_f32_16x16x32_bf16 v[0:3], v[138:141], v[146:149], v[0:3]
	s_waitcnt vmcnt(16)
	v_mfma_f32_16x16x32_bf16 v[4:7], v[150:153], v[154:157], v[4:7]
	s_waitcnt vmcnt(15)
	v_mfma_f32_16x16x32_bf16 v[0:3], v[150:153], v[158:161], v[0:3]
	s_waitcnt vmcnt(13)
	v_mfma_f32_16x16x32_bf16 v[4:7], v[162:165], v[166:169], v[4:7]
	s_waitcnt vmcnt(12)
	v_mfma_f32_16x16x32_bf16 v[0:3], v[162:165], v[170:173], v[0:3]
	s_waitcnt vmcnt(10)
	v_mfma_f32_16x16x32_bf16 v[4:7], v[174:177], v[178:181], v[4:7]
	s_waitcnt vmcnt(9)
	v_mfma_f32_16x16x32_bf16 v[0:3], v[174:177], v[182:185], v[0:3]
	s_waitcnt vmcnt(7)
	v_mfma_f32_16x16x32_bf16 v[4:7], v[190:193], v[194:197], v[4:7]
	s_waitcnt vmcnt(6)
	v_mfma_f32_16x16x32_bf16 v[0:3], v[190:193], v[198:201], v[0:3]
	s_waitcnt vmcnt(4)
	v_mfma_f32_16x16x32_bf16 v[4:7], v[204:207], v[208:211], v[4:7]
	s_waitcnt vmcnt(3)
	v_mfma_f32_16x16x32_bf16 v[0:3], v[204:207], v[212:215], v[0:3]
	s_waitcnt vmcnt(1)
	v_mfma_f32_16x16x32_bf16 v[4:7], v[216:219], v[220:223], v[4:7]
	s_waitcnt vmcnt(0)
	v_mfma_f32_16x16x32_bf16 v[0:3], v[216:219], v[224:227], v[0:3]
	s_cbranch_vccnz .LBB0_1269
	s_nop 4
	ds_write_b128 v18, v[4:7] offset:32768
	s_nop 0
	ds_write_b128 v18, v[0:3] offset:32784

; template <bool PAIR, class F>
; __device__ __forceinline__ void skinny(const bf16_t* A, int lda, const bf16_t* Bt, int ldb, int K, int tile_lo, int tile_hi, int kmode, int bx, int G, int tid_, LAS unsigned char* lds, F f) {
;     ...
;     for (int un = G - 1 - bx; un < nunits; un += G) {
;         const int rbp = un & 3, cgrp = un >> 2, tile = tile_lo + cgrp / GPT, cgp = (cgrp % GPT) * 4 + cgl;
;         const int n0 = tile * 256 + cgp * 16, row0 = MP + rbp * 32 + fr;
;         const bf16_t* ap = A + (size_t)row0 * lda + (kmode ? 256 * (tile >> 1) : 0) + fq * 8;
;         const bf16_t* bp = Bt + (size_t)(n0 + fr) * ldb + fq * 8;
;         f32x4 a00 = (f32x4){0.f, 0.f, 0.f, 0.f}, a01 = a00, a10 = a00, a11 = a00;
;         for (int k0 = kbeg; k0 < kbeg + Kh; k0 += 128) {
; #pragma unroll
;             for (int kk = 0; kk < 128; kk += 32) {
;                 const bf16x8 x0 = *(const bf16x8*)(ap + k0 + kk), x1 = *(const bf16x8*)(ap + (size_t)16 * lda + k0 + kk), b = *(const bf16x8*)(bp + k0 + kk);
;                 a00 = __builtin_amdgcn_mfma_f32_16x16x32_bf16(b, x0, a00, 0, 0, 0); a01 = __builtin_amdgcn_mfma_f32_16x16x32_bf16(b, x1, a01, 0, 0, 0);
;                 if (PAIR) { const bf16x8 b2 = *(const bf16x8*)(bp + (size_t)128 * ldb + k0 + kk);
;                     a10 = __builtin_amdgcn_mfma_f32_16x16x32_bf16(b2, x0, a10, 0, 0, 0); a11 = __builtin_amdgcn_mfma_f32_16x16x32_bf16(b2, x1, a11, 0, 0, 0); }
;             }
;         }
;         if (kh == 1) { X[0] = a00; X[1] = a01; if (PAIR) { X[2] = a10; X[3] = a11; } }
;         __syncthreads();
.LBB0_1449:
	s_ashr_i32 s22, s10, 2
	s_lshr_b32 s23, s22, 30
	s_add_i32 s24, s22, s23
	s_and_b32 s23, s24, 0x3fffffc
	s_sub_i32 s22, s22, s23
	s_lshl_b32 s22, s22, 6
	s_or_b32 s23, s22, s11
	s_and_b32 s22, s13, 0x60
	v_or_b32_e32 v0, s22, v14
	s_lshl_b32 s22, s24, 6
	s_and_b32 s22, s22, 0xffffff00
	s_add_i32 s24, s23, s22
	v_lshlrev_b32_e32 v17, 10, v0
	v_or_b32_e32 v0, s24, v14
	v_ashrrev_i32_e32 v1, 31, v0
	v_lshlrev_b64 v[0:1], 11, v[0:1]
	v_lshl_add_u64 v[62:63], v[12:13], 0, v[0:1]
	v_or_b32_e32 v4, 0x1000000, v17
	v_lshlrev_b32_e32 v8, 1, v4
	v_lshl_add_u64 v[216:217], v[10:11], 0, v[8:9]
	v_lshl_add_u64 v[218:219], v[216:217], 0, s[18:19]
	v_lshl_add_u64 v[220:221], v[216:217], 0, s[16:17]
	v_lshl_add_u64 v[222:223], v[220:221], 0, s[18:19]
	v_lshl_add_u64 v[224:225], s[6:7], 1, v[220:221]
	s_and_b64 vcc, exec, s[2:3]
	v_lshl_add_u64 v[226:227], s[8:9], 1, v[220:221]
	v_lshl_add_u64 v[230:231], s[14:15], 1, v[220:221]
	global_load_dwordx4 v[18:21], v[62:63], off
	global_load_dwordx4 v[22:25], v[218:219], off
	global_load_dwordx4 v[26:29], v[222:223], off
	global_load_dwordx4 v[30:33], v[62:63], off offset:64
	global_load_dwordx4 v[34:37], v[218:219], off offset:64
	global_load_dwordx4 v[38:41], v[222:223], off offset:64
	global_load_dwordx4 v[42:45], v[62:63], off offset:128
	global_load_dwordx4 v[46:49], v[218:219], off offset:128
	global_load_dwordx4 v[50:53], v[222:223], off offset:128
	global_load_dwordx4 v[54:57], v[62:63], off offset:192
	global_load_dwordx4 v[58:61], v[218:219], off offset:192
	global_load_dwordx4 v[64:67], v[222:223], off offset:192
	global_load_dwordx4 v[68:71], v[224:225], off
	global_load_dwordx4 v[72:75], v[62:63], off offset:256
	global_load_dwordx4 v[76:79], v[218:219], off offset:256
	global_load_dwordx4 v[80:83], v[62:63], off offset:320
	global_load_dwordx4 v[84:87], v[218:219], off offset:320
	global_load_dwordx4 v[88:91], v[62:63], off offset:384
	global_load_dwordx4 v[92:95], v[224:225], off offset:64
	global_load_dwordx4 v[96:99], v[218:219], off offset:384
	global_load_dwordx4 v[100:103], v[224:225], off offset:128
	global_load_dwordx4 v[104:107], v[62:63], off offset:448
	global_load_dwordx4 v[108:111], v[218:219], off offset:448
	global_load_dwordx4 v[112:115], v[224:225], off offset:192
	global_load_dwordx4 v[116:119], v[62:63], off offset:512
	global_load_dwordx4 v[120:123], v[218:219], off offset:512
	global_load_dwordx4 v[124:127], v[226:227], off
	global_load_dwordx4 v[128:131], v[62:63], off offset:576
	global_load_dwordx4 v[132:135], v[218:219], off offset:576
	global_load_dwordx4 v[136:139], v[226:227], off offset:64
	global_load_dwordx4 v[140:143], v[62:63], off offset:640
	global_load_dwordx4 v[146:149], v[218:219], off offset:640
	global_load_dwordx4 v[150:153], v[226:227], off offset:128
	global_load_dwordx4 v[154:157], v[62:63], off offset:704
	global_load_dwordx4 v[158:161], v[218:219], off offset:704
	global_load_dwordx4 v[162:165], v[226:227], off offset:192
	global_load_dwordx4 v[166:169], v[62:63], off offset:768
	global_load_dwordx4 v[170:173], v[218:219], off offset:768
	global_load_dwordx4 v[174:177], v[230:231], off
	global_load_dwordx4 v[178:181], v[62:63], off offset:832
	global_load_dwordx4 v[182:185], v[218:219], off offset:832
	global_load_dwordx4 v[186:189], v[230:231], off offset:64
	global_load_dwordx4 v[190:193], v[62:63], off offset:896
	global_load_dwordx4 v[194:197], v[218:219], off offset:896
	global_load_dwordx4 v[198:201], v[230:231], off offset:128
	global_load_dwordx4 v[204:207], v[62:63], off offset:960
	global_load_dwordx4 v[208:211], v[218:219], off offset:960
	global_load_dwordx4 v[212:215], v[230:231], off offset:192
	s_waitcnt vmcnt(46)
	v_mfma_f32_16x16x32_bf16 v[4:7], v[18:21], v[22:25], 0
	s_waitcnt vmcnt(45)
	v_mfma_f32_16x16x32_bf16 v[0:3], v[18:21], v[26:29], 0
	s_waitcnt vmcnt(43)
	v_mfma_f32_16x16x32_bf16 v[4:7], v[30:33], v[34:37], v[4:7]
	s_waitcnt vmcnt(42)
	v_mfma_f32_16x16x32_bf16 v[0:3], v[30:33], v[38:41], v[0:3]
	s_waitcnt vmcnt(40)
	v_mfma_f32_16x16x32_bf16 v[4:7], v[42:45], v[46:49], v[4:7]
	s_waitcnt vmcnt(39)
	v_mfma_f32_16x16x32_bf16 v[0:3], v[42:45], v[50:53], v[0:3]
	s_waitcnt vmcnt(37)
	v_mfma_f32_16x16x32_bf16 v[4:7], v[54:57], v[58:61], v[4:7]
	s_waitcnt vmcnt(36)
	v_mfma_f32_16x16x32_bf16 v[0:3], v[54:57], v[64:67], v[0:3]
	s_waitcnt vmcnt(33)
	v_mfma_f32_16x16x32_bf16 v[4:7], v[72:75], v[76:79], v[4:7]
	v_mfma_f32_16x16x32_bf16 v[0:3], v[72:75], v[68:71], v[0:3]
	s_waitcnt vmcnt(31)
	v_mfma_f32_16x16x32_bf16 v[4:7], v[80:83], v[84:87], v[4:7]
	s_waitcnt vmcnt(29)
	v_mfma_f32_16x16x32_bf16 v[0:3], v[80:83], v[92:95], v[0:3]
	s_waitcnt vmcnt(28)
	v_mfma_f32_16x16x32_bf16 v[4:7], v[88:91], v[96:99], v[4:7]
	s_waitcnt vmcnt(27)
	v_mfma_f32_16x16x32_bf16 v[0:3], v[88:91], v[100:103], v[0:3]
	s_waitcnt vmcnt(25)
	v_mfma_f32_16x16x32_bf16 v[4:7], v[104:107], v[108:111], v[4:7]
	s_waitcnt vmcnt(24)
	v_mfma_f32_16x16x32_bf16 v[0:3], v[104:107], v[112:115], v[0:3]
	s_waitcnt vmcnt(22)
	v_mfma_f32_16x16x32_bf16 v[4:7], v[116:119], v[120:123], v[4:7]
	s_waitcnt vmcnt(21)
	v_mfma_f32_16x16x32_bf16 v[0:3], v[116:119], v[124:127], v[0:3]
	s_waitcnt vmcnt(19)
	v_mfma_f32_16x16x32_bf16 v[4:7], v[128:131], v[132:135], v[4:7]
	s_waitcnt vmcnt(18)
	v_mfma_f32_16x16x32_bf16 v[0:3], v[128:131], v[136:139], v[0:3]
	s_waitcnt vmcnt(16)
	v_mfma_f32_16x16x32_bf16 v[4:7], v[140:143], v[146:149], v[4:7]
	s_waitcnt vmcnt(15)
	v_mfma_f32_16x16x32_bf16 v[0:3], v[140:143], v[150:153], v[0:3]
	s_waitcnt vmcnt(13)
	v_mfma_f32_16x16x32_bf16 v[4:7], v[154:157], v[158:161], v[4:7]
	s_waitcnt vmcnt(12)
	v_mfma_f32_16x16x32_bf16 v[0:3], v[154:157], v[162:165], v[0:3]
	s_waitcnt vmcnt(10)
	v_mfma_f32_16x16x32_bf16 v[4:7], v[166:169], v[170:173], v[4:7]
	s_waitcnt vmcnt(9)
	v_mfma_f32_16x16x32_bf16 v[0:3], v[166:169], v[174:177], v[0:3]
	s_waitcnt vmcnt(7)
	v_mfma_f32_16x16x32_bf16 v[4:7], v[178:181], v[182:185], v[4:7]
	s_waitcnt vmcnt(6)
	v_mfma_f32_16x16x32_bf16 v[0:3], v[178:181], v[186:189], v[0:3]
	s_waitcnt vmcnt(4)
	v_mfma_f32_16x16x32_bf16 v[4:7], v[190:193], v[194:197], v[4:7]
	s_waitcnt vmcnt(3)
	v_mfma_f32_16x16x32_bf16 v[0:3], v[190:193], v[198:201], v[0:3]
	s_waitcnt vmcnt(1)
	v_mfma_f32_16x16x32_bf16 v[4:7], v[204:207], v[208:211], v[4:7]
	s_waitcnt vmcnt(0)
	v_mfma_f32_16x16x32_bf16 v[0:3], v[204:207], v[212:215], v[0:3]
	s_cbranch_vccnz .LBB0_1451
	s_nop 4
	ds_write_b128 v16, v[4:7] offset:32768
	s_nop 0
	ds_write_b128 v16, v[0:3] offset:32784
